# PROJ1 GEMM: unit order changed so the last (partial) round is the 136 gate tiles; in gate-tile units the MFMA blocks of the padded columns are skipped (32 of 256 columns are real)
# baseline (speedup 1.0000x reference)
.LBB0_165:
	s_lshl_b32 s0, s33, 3
	s_and_b32 s0, s0, 0xf8
	s_ashr_i32 s1, s33, 5
	s_add_i32 s18, s0, s1
	s_ashr_i32 s19, s18, 31
	s_cmpk_lt_i32 s18, 0x1188
	s_cselect_b64 s[2:3], -1, 0
	s_cmpk_gt_i32 s18, 0x1187
	v_readfirstlane_b32 s20, v0
	s_cbranch_scc1 .LBB0_167
	s_and_b32 s0, s18, 7
	s_lshr_b32 s1, s18, 3
	s_mul_i32 s0, s0, 17
	s_cmp_lt_u32 s1, 0x220
	s_cbranch_scc0 .Lgt_gate0
	s_lshr_b32 s12, s1, 7
	s_lshl_b32 s10, s12, 2
	s_add_i32 s10, s10, s0
	s_and_b32 s1, s1, 0x7f
	s_cmp_eq_u32 s12, 4
	s_cbranch_scc1 .Lgt_last0
	s_and_b32 s12, s1, 3
	s_add_i32 s10, s10, s12
	s_lshr_b32 s12, s1, 2
	s_branch .Lgt_done0
.Lgt_last0:
	s_mov_b32 s12, s1
	s_branch .Lgt_done0
.Lgt_gate0:
	s_sub_i32 s1, s1, 0x220
	s_add_i32 s10, s0, s1
	s_movk_i32 s12, 32
.Lgt_done0:
.LBB0_167:
	v_readlane_b32 s0, v254, 0
	v_readlane_b32 s1, v254, 1
	s_load_dwordx4 s[24:27], s[0:1], 0x40
	s_load_dwordx2 s[4:5], s[0:1], 0x50
	v_readlane_b32 s6, v255, 22
	v_readlane_b32 s7, v255, 23
	s_mov_b32 s7, s93
	s_mul_i32 s0, s6, 0x6000
	s_mul_hi_u32 s1, s6, 0x6000
	s_waitcnt lgkmcnt(0)
	s_add_u32 s0, s24, s0
	v_writelane_b32 v255, s6, 22
	s_addc_u32 s1, s25, s1
	s_nop 0
	v_writelane_b32 v255, s7, 23
	s_lshl_b64 s[6:7], s[6:7], 13
	s_add_u32 s36, s26, s6
	s_addc_u32 s37, s27, s7
	s_andn2_b64 vcc, exec, s[2:3]
	s_cbranch_vccnz .LBB0_260
	s_waitcnt vmcnt(0)
	v_ashrrev_i32_e32 v2, 31, v0
	v_lshrrev_b32_e32 v2, 26, v2
	v_add_u32_e32 v2, v0, v2
	v_ashrrev_i32_e32 v10, 6, v2
	v_bfe_i32 v2, v0, 27, 1
	v_lshlrev_b32_e32 v1, 4, v0
	v_lshrrev_b32_e32 v2, 22, v2
	v_add_u32_e32 v2, v1, v2
	v_and_b32_e32 v2, 0xfffffc00, v2
	v_sub_u32_e32 v2, v1, v2
	v_lshrrev_b32_e32 v3, 4, v2
	v_bitop3_b32 v2, v3, v2, 32 bitop3:0x6c
	v_ashrrev_i32_e32 v4, 31, v2
	v_lshrrev_b32_e32 v4, 26, v4
	v_add_u32_e32 v4, v2, v4
	v_lshlrev_b32_e32 v3, 3, v10
	v_ashrrev_i32_e32 v11, 6, v4
	v_and_b32_e32 v4, 0xc0, v4
	v_and_b32_e32 v3, -16, v3
	v_sub_u32_e32 v2, v2, v4
	v_add_u32_e32 v3, v11, v3
	v_ashrrev_i16_sdwa v2, v228, sext(v2) dst_sel:DWORD dst_unused:UNUSED_PAD src0_sel:DWORD src1_sel:BYTE_0
	v_lshlrev_b32_e32 v5, 5, v10
	v_bfe_i32 v12, v2, 0, 16
	v_lshlrev_b32_e32 v2, 1, v3
	v_lshrrev_b32_e32 v4, 2, v3
	v_and_b32_e32 v6, 3, v11
	s_mov_b32 s2, 0xfffe0
	v_and_b32_e32 v5, 32, v5
	v_and_b32_e32 v2, 24, v2
	v_and_b32_e32 v4, 4, v4
	v_and_or_b32 v6, v3, s2, v6
	v_or3_b32 v2, v6, v4, v2
	v_add_lshl_u32 v4, v5, v12, 1
	v_add_u32_e32 v1, 0x2000, v1
	v_lshl_add_u32 v160, v2, 12, v4
	v_ashrrev_i32_e32 v2, 31, v1
	v_lshrrev_b32_e32 v2, 22, v2
	v_add_u32_e32 v2, v1, v2
	v_ashrrev_i32_e32 v13, 10, v2
	v_mul_i32_i24_e32 v2, 0x400, v13
	v_sub_u32_e32 v1, v1, v2
	v_lshrrev_b32_e32 v2, 4, v1
	v_bitop3_b32 v1, v2, v1, 32 bitop3:0x6c
	v_lshl_add_u32 v158, v3, 12, v4
	v_ashrrev_i32_e32 v3, 31, v1
	v_lshrrev_b32_e32 v3, 26, v3
	v_lshlrev_b32_e32 v2, 3, v13
	v_add_u32_e32 v3, v1, v3
	v_and_b32_e32 v2, -16, v2
	v_ashrrev_i32_e32 v14, 6, v3
	s_ashr_i32 s38, s20, 6
	v_add_u32_e32 v2, v14, v2
	v_and_b32_e32 v3, 0xc0, v3
	v_and_b32_e32 v5, 3, v14
	s_ashr_i32 s11, s10, 31
	s_ashr_i32 s13, s12, 31
	v_writelane_b32 v255, s33, 30
	v_sub_u32_e32 v1, v1, v3
	v_and_or_b32 v5, v2, s2, v5
	s_ashr_i32 s28, s20, 8
	s_lshl_b32 s33, s38, 10
	s_lshl_b64 s[2:3], s[10:11], 20
	s_lshl_b64 s[6:7], s[12:13], 20
	v_readlane_b32 s8, v254, 21
	v_ashrrev_i16_sdwa v1, v228, sext(v1) dst_sel:DWORD dst_unused:UNUSED_PAD src0_sel:DWORD src1_sel:BYTE_0
	v_readlane_b32 s9, v254, 22
	s_add_u32 s14, s8, s6
	v_lshlrev_b32_e32 v4, 5, v13
	v_bfe_i32 v15, v1, 0, 16
	v_lshlrev_b32_e32 v1, 1, v2
	v_lshrrev_b32_e32 v3, 2, v2
	s_addc_u32 s15, s9, s7
	s_add_i32 s40, s33, 0
	v_and_b32_e32 v4, 32, v4
	v_and_b32_e32 v1, 24, v1
	v_and_b32_e32 v3, 4, v3
	s_add_i32 m0, s40, 0x10000
	v_or3_b32 v1, v5, v3, v1
	v_add_lshl_u32 v3, v4, v15, 1
	global_load_lds_dwordx4 v160, s[14:15]
	s_add_i32 m0, s40, 0x12000
	v_lshl_add_u32 v164, v1, 12, v3
	s_add_u32 s6, s14, 0x80000
	global_load_lds_dwordx4 v164, s[14:15]
	s_addc_u32 s7, s15, 0
	s_add_i32 m0, s40, 0x14000
	v_lshl_add_u32 v162, v2, 12, v3
	global_load_lds_dwordx4 v160, s[6:7]
	s_add_i32 m0, s40, 0x16000
	v_mov_b32_e32 v161, v191
	global_load_lds_dwordx4 v164, s[6:7]
	v_readlane_b32 s6, v254, 17
	v_readlane_b32 s7, v254, 18
	s_add_u32 s8, s6, s2
	s_addc_u32 s9, s7, s3
	s_add_i32 s41, s40, 0x2000
	s_mov_b32 m0, s40
	s_add_u32 s2, s8, 0x80000
	global_load_lds_dwordx4 v158, s[8:9]
	s_mov_b32 m0, s41
	s_addc_u32 s3, s9, 0
	s_add_i32 s42, s40, 0x4000
	global_load_lds_dwordx4 v162, s[8:9]
	s_mov_b32 m0, s42
	s_add_i32 s43, s40, 0x6000
	global_load_lds_dwordx4 v158, s[2:3]
	s_mov_b32 m0, s43
	v_mov_b32_e32 v165, v191
	global_load_lds_dwordx4 v162, s[2:3]
	v_mov_b32_e32 v159, v191
	v_mov_b32_e32 v163, v191
	s_cmp_eq_u32 s28, 1
	v_lshl_add_u64 v[8:9], s[14:15], 0, v[160:161]
	v_lshl_add_u64 v[6:7], s[14:15], 0, v[164:165]
	v_lshl_add_u64 v[2:3], s[8:9], 0, v[158:159]
	s_cselect_b64 s[2:3], -1, 0
	s_cmp_lg_u32 s28, 1
	v_lshl_add_u64 v[4:5], s[8:9], 0, v[162:163]
	s_cbranch_scc1 .LBB0_170
	s_barrier

.LBB0_173:
	s_cmp_eq_u32 s22, 0
	s_cselect_b32 s32, 3, 1
	s_cmp_eq_u32 s12, 32
	s_cselect_b32 s32, s32, 0
	s_add_i32 s92, s92, 1
	s_lshl_b64 s[6:7], s[92:93], 8
	s_add_u32 s52, s6, s18
	s_addc_u32 s53, s7, s19
	v_mov_b64_e32 v[2:3], 0x1188
	v_cmp_lt_i64_e64 s[6:7], s[52:53], v[2:3]
	v_mov_b64_e32 v[2:3], 0x1187
	v_cmp_gt_i64_e32 vcc, s[52:53], v[2:3]
	s_cbranch_vccnz .LBB0_175
	s_and_b32 s11, s52, 7
	s_lshr_b32 s13, s52, 3
	s_mul_i32 s11, s11, 17
	s_cmp_lt_u32 s13, 0x220
	s_cbranch_scc0 .Lgt_gate1
	s_lshr_b32 s60, s13, 7
	s_lshl_b32 s56, s60, 2
	s_add_i32 s56, s56, s11
	s_and_b32 s13, s13, 0x7f
	s_cmp_eq_u32 s60, 4
	s_cbranch_scc1 .Lgt_last1
	s_and_b32 s60, s13, 3
	s_add_i32 s56, s56, s60
	s_lshr_b32 s60, s13, 2
	s_branch .Lgt_done1
.Lgt_last1:
	s_mov_b32 s60, s13
	s_branch .Lgt_done1
.Lgt_gate1:
	s_sub_i32 s13, s13, 0x220
	s_add_i32 s56, s11, s13
	s_movk_i32 s60, 32
.Lgt_done1:
.LBB0_175:
	s_ashr_i32 s57, s56, 31
	s_lshl_b64 s[52:53], s[56:57], 20
	v_readlane_b32 s66, v254, 17
	v_readlane_b32 s67, v254, 18
	s_add_u32 s66, s66, s52
	s_addc_u32 s67, s67, s53
	s_and_b64 s[52:53], s[6:7], exec
	s_cselect_b32 s11, s67, s9
	s_cselect_b32 s13, s66, s8
	s_ashr_i32 s61, s60, 31
	s_lshl_b64 s[52:53], s[60:61], 20
	v_readlane_b32 s68, v254, 21
	v_readlane_b32 s69, v254, 22
	s_add_u32 s88, s68, s52
	s_addc_u32 s89, s69, s53
	s_and_b64 s[52:53], s[6:7], exec
	s_cselect_b32 s57, s89, s15
	s_cselect_b32 s61, s88, s14
	s_add_u32 s8, s8, 0x80080
	s_addc_u32 s9, s9, 0
	s_add_u32 s68, s14, 0x100
	s_addc_u32 s69, s15, 0
	s_mov_b32 s90, -2
	s_add_u32 s14, s8, 0xfff80080
	s_addc_u32 s15, s9, -1
	s_add_i32 s91, 0, 0x10000
	s_cmp_eq_u32 s90, 28
	s_cselect_b32 s53, s11, s15
	s_cselect_b32 s52, s13, s14
	v_add_u32_e32 v14, s91, v188
	s_cselect_b32 s15, s57, s69
	s_cselect_b32 s14, s61, s68
	s_add_i32 s96, 0, 0x14000
	ds_read_b128 v[6:9], v14
	ds_read_b128 v[10:13], v14 offset:1024
	ds_read_b128 v[140:143], v14 offset:2048
	ds_read_b128 v[144:147], v14 offset:3072
	v_add_u32_e32 v14, s96, v188
	ds_read_b128 v[148:151], v14
	ds_read_b128 v[152:155], v14 offset:1024
	ds_read_b128 v[180:183], v14 offset:2048
	ds_read_b128 v[208:211], v14 offset:3072
	v_lshl_add_u64 v[14:15], s[8:9], 0, v[176:177]
	s_add_i32 m0, s40, 0xc000
	ds_read_b128 v[212:215], v206
	ds_read_b128 v[216:219], v206 offset:1024
	ds_read_b128 v[220:223], v206 offset:2048
	ds_read_b128 v[224:227], v206 offset:3072
	ds_read_b128 v[238:241], v206 offset:4096
	ds_read_b128 v[242:245], v206 offset:5120
	ds_read_b128 v[246:249], v206 offset:6144
	ds_read_b128 v[250:253], v206 offset:7168
	global_load_lds_dwordx4 v[14:15], off
	v_lshl_add_u64 v[14:15], s[8:9], 0, v[178:179]
	s_add_i32 m0, s40, 0xe000
	s_nop 0
	global_load_lds_dwordx4 v[14:15], off
	s_waitcnt vmcnt(8)
	s_waitcnt lgkmcnt(0)
	s_barrier
	s_bitcmp1_b32 s32, 1
	s_cbranch_scc1 .Lgsk_0
	s_setprio 1
	s_waitcnt lgkmcnt(0)
	v_mfma_f32_16x16x32_bf16 v[136:139], v[6:9], v[212:215], 0
	v_mfma_f32_16x16x32_bf16 v[104:107], v[140:143], v[212:215], 0
	v_mfma_f32_16x16x32_bf16 v[132:135], v[6:9], v[220:223], 0
	v_mfma_f32_16x16x32_bf16 v[100:103], v[140:143], v[220:223], 0
	v_mfma_f32_16x16x32_bf16 v[128:131], v[6:9], v[238:241], 0
	v_mfma_f32_16x16x32_bf16 v[96:99], v[140:143], v[238:241], 0
	v_mfma_f32_16x16x32_bf16 v[124:127], v[6:9], v[246:249], 0
	v_mfma_f32_16x16x32_bf16 v[92:95], v[140:143], v[246:249], 0
	v_mfma_f32_16x16x32_bf16 v[136:139], v[10:13], v[216:219], v[136:139]
	v_mfma_f32_16x16x32_bf16 v[104:107], v[144:147], v[216:219], v[104:107]
	v_mfma_f32_16x16x32_bf16 v[132:135], v[10:13], v[224:227], v[132:135]
	v_mfma_f32_16x16x32_bf16 v[100:103], v[144:147], v[224:227], v[100:103]
	v_mfma_f32_16x16x32_bf16 v[128:131], v[10:13], v[242:245], v[128:131]
	v_mfma_f32_16x16x32_bf16 v[96:99], v[144:147], v[242:245], v[96:99]
	v_mfma_f32_16x16x32_bf16 v[124:127], v[10:13], v[250:253], v[124:127]
	v_mfma_f32_16x16x32_bf16 v[92:95], v[144:147], v[250:253], v[92:95]
	s_setprio 0
.Lgsk_0:
	s_bitcmp1_b32 s32, 0
	s_cbranch_scc1 .Lgsk_1
	s_setprio 1
	v_mfma_f32_16x16x32_bf16 v[72:75], v[148:151], v[212:215], 0
	v_mfma_f32_16x16x32_bf16 v[40:43], v[180:183], v[212:215], 0
	v_mfma_f32_16x16x32_bf16 v[68:71], v[148:151], v[220:223], 0
	v_mfma_f32_16x16x32_bf16 v[36:39], v[180:183], v[220:223], 0
	v_mfma_f32_16x16x32_bf16 v[64:67], v[148:151], v[238:241], 0
	v_mfma_f32_16x16x32_bf16 v[32:35], v[180:183], v[238:241], 0
	v_mfma_f32_16x16x32_bf16 v[60:63], v[148:151], v[246:249], 0
	v_mfma_f32_16x16x32_bf16 v[28:31], v[180:183], v[246:249], 0
	v_mfma_f32_16x16x32_bf16 v[72:75], v[152:155], v[216:219], v[72:75]
	v_mfma_f32_16x16x32_bf16 v[40:43], v[208:211], v[216:219], v[40:43]
	v_mfma_f32_16x16x32_bf16 v[68:71], v[152:155], v[224:227], v[68:71]
	v_mfma_f32_16x16x32_bf16 v[36:39], v[208:211], v[224:227], v[36:39]
	v_mfma_f32_16x16x32_bf16 v[64:67], v[152:155], v[242:245], v[64:67]
	v_mfma_f32_16x16x32_bf16 v[32:35], v[208:211], v[242:245], v[32:35]
	v_mfma_f32_16x16x32_bf16 v[60:63], v[152:155], v[250:253], v[60:63]
	v_mfma_f32_16x16x32_bf16 v[28:31], v[208:211], v[250:253], v[28:31]
	s_setprio 0
.Lgsk_1:
	s_barrier
	s_add_i32 s91, s91, s33
	v_lshl_add_u64 v[156:157], s[14:15], 0, v[160:161]
	s_mov_b32 m0, s91
	ds_read_b128 v[212:215], v206 offset:16384
	ds_read_b128 v[216:219], v206 offset:17408
	ds_read_b128 v[220:223], v206 offset:18432
	ds_read_b128 v[224:227], v206 offset:19456
	ds_read_b128 v[238:241], v206 offset:20480
	ds_read_b128 v[242:245], v206 offset:21504
	ds_read_b128 v[246:249], v206 offset:22528
	ds_read_b128 v[250:253], v206 offset:23552
	global_load_lds_dwordx4 v[156:157], off
	s_add_i32 m0, s91, 0x2000
	s_add_u32 vcc_lo, s14, 0x80000
	v_lshl_add_u64 v[184:185], s[14:15], 0, v[164:165]
	s_addc_u32 vcc_hi, s15, 0
	s_add_i32 s91, s96, s33
	global_load_lds_dwordx4 v[184:185], off
	v_lshl_add_u64 v[14:15], vcc, 0, v[160:161]
	s_mov_b32 m0, s91
	v_lshl_add_u64 v[196:197], s[52:53], 0, v[158:159]
	global_load_lds_dwordx4 v[14:15], off
	v_lshl_add_u64 v[14:15], vcc, 0, v[164:165]
	s_add_i32 m0, s91, 0x2000
	v_lshl_add_u64 v[198:199], s[52:53], 0, v[162:163]
	global_load_lds_dwordx4 v[14:15], off
	s_mov_b32 m0, s40
	s_nop 0
	global_load_lds_dwordx4 v[196:197], off
	s_mov_b32 m0, s41
	s_nop 0
	global_load_lds_dwordx4 v[198:199], off
	s_waitcnt vmcnt(8)
	s_waitcnt lgkmcnt(0)
	s_barrier
	s_bitcmp1_b32 s32, 1
	s_cbranch_scc1 .Lgsk_2
	s_setprio 1
	s_waitcnt lgkmcnt(0)
	v_mfma_f32_16x16x32_bf16 v[120:123], v[6:9], v[212:215], 0
	v_mfma_f32_16x16x32_bf16 v[88:91], v[140:143], v[212:215], 0
	v_mfma_f32_16x16x32_bf16 v[116:119], v[6:9], v[220:223], 0
	v_mfma_f32_16x16x32_bf16 v[84:87], v[140:143], v[220:223], 0
	v_mfma_f32_16x16x32_bf16 v[112:115], v[6:9], v[238:241], 0
	v_mfma_f32_16x16x32_bf16 v[80:83], v[140:143], v[238:241], 0
	v_mfma_f32_16x16x32_bf16 v[6:9], v[6:9], v[246:249], 0
	v_mfma_f32_16x16x32_bf16 v[120:123], v[10:13], v[216:219], v[120:123]
	v_mfma_f32_16x16x32_bf16 v[88:91], v[144:147], v[216:219], v[88:91]
	v_mfma_f32_16x16x32_bf16 v[116:119], v[10:13], v[224:227], v[116:119]
	v_mfma_f32_16x16x32_bf16 v[84:87], v[144:147], v[224:227], v[84:87]
	v_mfma_f32_16x16x32_bf16 v[112:115], v[10:13], v[242:245], v[112:115]
	v_mfma_f32_16x16x32_bf16 v[80:83], v[144:147], v[242:245], v[80:83]
	v_mfma_f32_16x16x32_bf16 v[6:9], v[10:13], v[250:253], v[6:9]
	v_mfma_f32_16x16x32_bf16 v[10:13], v[140:143], v[246:249], 0
	v_mfma_f32_16x16x32_bf16 v[10:13], v[144:147], v[250:253], v[10:13]
	s_setprio 0
.Lgsk_2:
	s_bitcmp1_b32 s32, 0
	s_cbranch_scc1 .Lgsk_3
	s_setprio 1
	v_mfma_f32_16x16x32_bf16 v[56:59], v[148:151], v[212:215], 0
	v_mfma_f32_16x16x32_bf16 v[24:27], v[180:183], v[212:215], 0
	v_mfma_f32_16x16x32_bf16 v[52:55], v[148:151], v[220:223], 0
	v_mfma_f32_16x16x32_bf16 v[20:23], v[180:183], v[220:223], 0
	v_mfma_f32_16x16x32_bf16 v[48:51], v[148:151], v[238:241], 0
	v_mfma_f32_16x16x32_bf16 v[14:17], v[180:183], v[238:241], 0
	v_mfma_f32_16x16x32_bf16 v[44:47], v[148:151], v[246:249], 0
	v_mfma_f32_16x16x32_bf16 v[2:5], v[180:183], v[246:249], 0
	v_mfma_f32_16x16x32_bf16 v[56:59], v[152:155], v[216:219], v[56:59]
	v_mfma_f32_16x16x32_bf16 v[24:27], v[208:211], v[216:219], v[24:27]
	v_mfma_f32_16x16x32_bf16 v[52:55], v[152:155], v[224:227], v[52:55]
	v_mfma_f32_16x16x32_bf16 v[20:23], v[208:211], v[224:227], v[20:23]
	v_mfma_f32_16x16x32_bf16 v[48:51], v[152:155], v[242:245], v[48:51]
	v_mfma_f32_16x16x32_bf16 v[14:17], v[208:211], v[242:245], v[14:17]
	v_mfma_f32_16x16x32_bf16 v[44:47], v[152:155], v[250:253], v[44:47]
	v_mfma_f32_16x16x32_bf16 v[2:5], v[208:211], v[250:253], v[2:5]
	s_setprio 0
.Lgsk_3:
	s_barrier
	s_add_i32 s91, 0, 0x18000
	v_add_u32_e32 v18, s91, v188
	s_add_i32 s96, 0, 0x1c000
	ds_read_b128 v[76:79], v18
	ds_read_b128 v[108:111], v18 offset:1024
	ds_read_b128 v[140:143], v18 offset:2048
	ds_read_b128 v[144:147], v18 offset:3072
	v_add_u32_e32 v18, s96, v188
	ds_read_b128 v[148:151], v18
	ds_read_b128 v[152:155], v18 offset:1024
	ds_read_b128 v[180:183], v18 offset:2048
	ds_read_b128 v[208:211], v18 offset:3072
	s_add_u32 s52, s52, 0x80000
	s_addc_u32 s53, s53, 0
	s_mov_b32 m0, s42
	v_lshl_add_u64 v[18:19], s[52:53], 0, v[158:159]
	ds_read_b128 v[212:215], v206 offset:32768
	ds_read_b128 v[216:219], v206 offset:33792
	ds_read_b128 v[220:223], v206 offset:34816
	ds_read_b128 v[224:227], v206 offset:35840
	ds_read_b128 v[238:241], v206 offset:36864
	ds_read_b128 v[242:245], v206 offset:37888
	ds_read_b128 v[246:249], v206 offset:38912
	ds_read_b128 v[250:253], v206 offset:39936
	global_load_lds_dwordx4 v[18:19], off
	v_lshl_add_u64 v[18:19], s[52:53], 0, v[162:163]
	s_mov_b32 m0, s43
	s_nop 0
	global_load_lds_dwordx4 v[18:19], off
	s_waitcnt vmcnt(8)
	s_waitcnt lgkmcnt(0)
	s_barrier
	s_bitcmp1_b32 s32, 1
	s_cbranch_scc1 .Lgsk_4
	s_setprio 1
	s_waitcnt lgkmcnt(0)
	v_mfma_f32_16x16x32_bf16 v[136:139], v[76:79], v[212:215], v[136:139]
	v_mfma_f32_16x16x32_bf16 v[104:107], v[140:143], v[212:215], v[104:107]
	v_mfma_f32_16x16x32_bf16 v[132:135], v[76:79], v[220:223], v[132:135]
	v_mfma_f32_16x16x32_bf16 v[100:103], v[140:143], v[220:223], v[100:103]
	v_mfma_f32_16x16x32_bf16 v[128:131], v[76:79], v[238:241], v[128:131]
	v_mfma_f32_16x16x32_bf16 v[96:99], v[140:143], v[238:241], v[96:99]
	v_mfma_f32_16x16x32_bf16 v[124:127], v[76:79], v[246:249], v[124:127]
	v_mfma_f32_16x16x32_bf16 v[92:95], v[140:143], v[246:249], v[92:95]
	v_mfma_f32_16x16x32_bf16 v[136:139], v[108:111], v[216:219], v[136:139]
	v_mfma_f32_16x16x32_bf16 v[104:107], v[144:147], v[216:219], v[104:107]
	v_mfma_f32_16x16x32_bf16 v[132:135], v[108:111], v[224:227], v[132:135]
	v_mfma_f32_16x16x32_bf16 v[100:103], v[144:147], v[224:227], v[100:103]
	v_mfma_f32_16x16x32_bf16 v[128:131], v[108:111], v[242:245], v[128:131]
	v_mfma_f32_16x16x32_bf16 v[96:99], v[144:147], v[242:245], v[96:99]
	v_mfma_f32_16x16x32_bf16 v[124:127], v[108:111], v[250:253], v[124:127]
	v_mfma_f32_16x16x32_bf16 v[92:95], v[144:147], v[250:253], v[92:95]
	s_setprio 0
.Lgsk_4:
	s_bitcmp1_b32 s32, 0
	s_cbranch_scc1 .Lgsk_5
	s_setprio 1
	v_mfma_f32_16x16x32_bf16 v[72:75], v[148:151], v[212:215], v[72:75]
	v_mfma_f32_16x16x32_bf16 v[40:43], v[180:183], v[212:215], v[40:43]
	v_mfma_f32_16x16x32_bf16 v[68:71], v[148:151], v[220:223], v[68:71]
	v_mfma_f32_16x16x32_bf16 v[36:39], v[180:183], v[220:223], v[36:39]
	v_mfma_f32_16x16x32_bf16 v[64:67], v[148:151], v[238:241], v[64:67]
	v_mfma_f32_16x16x32_bf16 v[32:35], v[180:183], v[238:241], v[32:35]
	v_mfma_f32_16x16x32_bf16 v[60:63], v[148:151], v[246:249], v[60:63]
	v_mfma_f32_16x16x32_bf16 v[28:31], v[180:183], v[246:249], v[28:31]
	v_mfma_f32_16x16x32_bf16 v[72:75], v[152:155], v[216:219], v[72:75]
	v_mfma_f32_16x16x32_bf16 v[40:43], v[208:211], v[216:219], v[40:43]
	v_mfma_f32_16x16x32_bf16 v[68:71], v[152:155], v[224:227], v[68:71]
	v_mfma_f32_16x16x32_bf16 v[36:39], v[208:211], v[224:227], v[36:39]
	v_mfma_f32_16x16x32_bf16 v[64:67], v[152:155], v[242:245], v[64:67]
	v_mfma_f32_16x16x32_bf16 v[32:35], v[208:211], v[242:245], v[32:35]
	v_mfma_f32_16x16x32_bf16 v[60:63], v[152:155], v[250:253], v[60:63]
	v_mfma_f32_16x16x32_bf16 v[28:31], v[208:211], v[250:253], v[28:31]
	s_setprio 0
.Lgsk_5:
	s_barrier
	s_add_i32 s52, s91, s33
	v_lshl_add_u64 v[18:19], v[156:157], 0, s[58:59]
	s_mov_b32 m0, s52
	ds_read_b128 v[212:215], v206 offset:49152
	ds_read_b128 v[216:219], v206 offset:50176
	ds_read_b128 v[220:223], v206 offset:51200
	ds_read_b128 v[224:227], v206 offset:52224
	ds_read_b128 v[238:241], v206 offset:53248
	ds_read_b128 v[242:245], v206 offset:54272
	ds_read_b128 v[246:249], v206 offset:55296
	ds_read_b128 v[250:253], v206 offset:56320
	global_load_lds_dwordx4 v[18:19], off
	s_add_i32 m0, s52, 0x2000
	s_add_u32 s14, s14, 0x80080
	v_lshl_add_u64 v[18:19], v[184:185], 0, s[58:59]
	s_addc_u32 s15, s15, 0
	s_add_i32 s52, s96, s33
	global_load_lds_dwordx4 v[18:19], off
	v_lshl_add_u64 v[18:19], s[14:15], 0, v[160:161]
	s_mov_b32 m0, s52
	s_nop 0
	global_load_lds_dwordx4 v[18:19], off
	v_lshl_add_u64 v[18:19], s[14:15], 0, v[164:165]
	s_add_i32 m0, s52, 0x2000
	s_nop 0
	global_load_lds_dwordx4 v[18:19], off
	v_lshl_add_u64 v[18:19], v[196:197], 0, s[58:59]
	s_mov_b32 m0, s55
	s_nop 0
	global_load_lds_dwordx4 v[18:19], off
	v_lshl_add_u64 v[18:19], v[198:199], 0, s[58:59]
	s_mov_b32 m0, s77
	s_nop 0
	global_load_lds_dwordx4 v[18:19], off
	s_waitcnt vmcnt(8)
	s_waitcnt lgkmcnt(0)
	s_barrier
	s_bitcmp1_b32 s32, 1
	s_cbranch_scc1 .Lgsk_6
	s_setprio 1
	s_waitcnt lgkmcnt(0)
	v_mfma_f32_16x16x32_bf16 v[120:123], v[76:79], v[212:215], v[120:123]
	v_mfma_f32_16x16x32_bf16 v[116:119], v[76:79], v[220:223], v[116:119]
	v_mfma_f32_16x16x32_bf16 v[112:115], v[76:79], v[238:241], v[112:115]
	v_mfma_f32_16x16x32_bf16 v[6:9], v[76:79], v[246:249], v[6:9]
	v_mfma_f32_16x16x32_bf16 v[120:123], v[108:111], v[216:219], v[120:123]
	v_mfma_f32_16x16x32_bf16 v[88:91], v[140:143], v[212:215], v[88:91]
	v_mfma_f32_16x16x32_bf16 v[116:119], v[108:111], v[224:227], v[116:119]
	v_mfma_f32_16x16x32_bf16 v[84:87], v[140:143], v[220:223], v[84:87]
	v_mfma_f32_16x16x32_bf16 v[112:115], v[108:111], v[242:245], v[112:115]
	v_mfma_f32_16x16x32_bf16 v[80:83], v[140:143], v[238:241], v[80:83]
	v_mfma_f32_16x16x32_bf16 v[108:111], v[108:111], v[250:253], v[6:9]
	v_mfma_f32_16x16x32_bf16 v[6:9], v[140:143], v[246:249], v[10:13]
	v_mfma_f32_16x16x32_bf16 v[88:91], v[144:147], v[216:219], v[88:91]
	v_mfma_f32_16x16x32_bf16 v[84:87], v[144:147], v[224:227], v[84:87]
	v_mfma_f32_16x16x32_bf16 v[80:83], v[144:147], v[242:245], v[80:83]
	v_mfma_f32_16x16x32_bf16 v[76:79], v[144:147], v[250:253], v[6:9]
	s_setprio 0
.Lgsk_6:
	s_bitcmp1_b32 s32, 0
	s_cbranch_scc1 .Lgsk_7
	s_setprio 1
	v_mfma_f32_16x16x32_bf16 v[6:9], v[148:151], v[212:215], v[56:59]
	v_mfma_f32_16x16x32_bf16 v[56:59], v[152:155], v[216:219], v[6:9]
	v_mfma_f32_16x16x32_bf16 v[6:9], v[180:183], v[212:215], v[24:27]
	v_mfma_f32_16x16x32_bf16 v[24:27], v[208:211], v[216:219], v[6:9]
	v_mfma_f32_16x16x32_bf16 v[6:9], v[148:151], v[220:223], v[52:55]
	v_mfma_f32_16x16x32_bf16 v[52:55], v[152:155], v[224:227], v[6:9]
	v_mfma_f32_16x16x32_bf16 v[6:9], v[180:183], v[220:223], v[20:23]
	v_mfma_f32_16x16x32_bf16 v[20:23], v[208:211], v[224:227], v[6:9]
	v_mfma_f32_16x16x32_bf16 v[6:9], v[148:151], v[238:241], v[48:51]
	v_mfma_f32_16x16x32_bf16 v[48:51], v[152:155], v[242:245], v[6:9]
	v_mfma_f32_16x16x32_bf16 v[6:9], v[180:183], v[238:241], v[14:17]
	v_mfma_f32_16x16x32_bf16 v[16:19], v[208:211], v[242:245], v[6:9]
	v_mfma_f32_16x16x32_bf16 v[6:9], v[148:151], v[246:249], v[44:47]
	v_mfma_f32_16x16x32_bf16 v[2:5], v[180:183], v[246:249], v[2:5]
	v_mfma_f32_16x16x32_bf16 v[44:47], v[152:155], v[250:253], v[6:9]
	v_mfma_f32_16x16x32_bf16 v[2:5], v[208:211], v[250:253], v[2:5]
	s_setprio 0
.Lgsk_7:
	s_barrier
	s_add_i32 s90, s90, 2
	s_add_u32 s8, s8, 0x100
	s_addc_u32 s9, s9, 0
	s_add_u32 s68, s68, 0x100
	s_addc_u32 s69, s69, 0
	s_cmp_gt_u32 s90, 29
	s_cbranch_scc1 .Lpeel_done_0
.LBB0_176:
	s_add_u32 s14, s8, 0xfff80080
	s_addc_u32 s15, s9, -1
	s_add_i32 s91, 0, 0x10000
	s_cmp_eq_u32 s90, 28
	s_cselect_b32 s53, s11, s15
	s_cselect_b32 s52, s13, s14
	v_add_u32_e32 v14, s91, v188
	s_cselect_b32 s15, s57, s69
	s_cselect_b32 s14, s61, s68
	s_add_i32 s96, 0, 0x14000
	ds_read_b128 v[6:9], v14
	ds_read_b128 v[10:13], v14 offset:1024
	ds_read_b128 v[140:143], v14 offset:2048
	ds_read_b128 v[144:147], v14 offset:3072
	v_add_u32_e32 v14, s96, v188
	ds_read_b128 v[148:151], v14
	ds_read_b128 v[152:155], v14 offset:1024
	ds_read_b128 v[180:183], v14 offset:2048
	ds_read_b128 v[208:211], v14 offset:3072
	v_lshl_add_u64 v[14:15], s[8:9], 0, v[176:177]
	s_add_i32 m0, s40, 0xc000
	ds_read_b128 v[212:215], v206
	ds_read_b128 v[216:219], v206 offset:1024
	ds_read_b128 v[220:223], v206 offset:2048
	ds_read_b128 v[224:227], v206 offset:3072
	ds_read_b128 v[238:241], v206 offset:4096
	ds_read_b128 v[242:245], v206 offset:5120
	ds_read_b128 v[246:249], v206 offset:6144
	ds_read_b128 v[250:253], v206 offset:7168
	global_load_lds_dwordx4 v[14:15], off
	v_lshl_add_u64 v[14:15], s[8:9], 0, v[178:179]
	s_add_i32 m0, s40, 0xe000
	s_nop 0
	global_load_lds_dwordx4 v[14:15], off
	s_waitcnt vmcnt(8)
	s_waitcnt lgkmcnt(0)
	s_barrier
	s_bitcmp1_b32 s32, 1
	s_cbranch_scc1 .Lgsk_8
	s_setprio 1
	s_waitcnt lgkmcnt(0)
	v_mfma_f32_16x16x32_bf16 v[136:139], v[6:9], v[212:215], v[136:139]
	v_mfma_f32_16x16x32_bf16 v[104:107], v[140:143], v[212:215], v[104:107]
	v_mfma_f32_16x16x32_bf16 v[132:135], v[6:9], v[220:223], v[132:135]
	v_mfma_f32_16x16x32_bf16 v[100:103], v[140:143], v[220:223], v[100:103]
	v_mfma_f32_16x16x32_bf16 v[128:131], v[6:9], v[238:241], v[128:131]
	v_mfma_f32_16x16x32_bf16 v[96:99], v[140:143], v[238:241], v[96:99]
	v_mfma_f32_16x16x32_bf16 v[124:127], v[6:9], v[246:249], v[124:127]
	v_mfma_f32_16x16x32_bf16 v[92:95], v[140:143], v[246:249], v[92:95]
	v_mfma_f32_16x16x32_bf16 v[136:139], v[10:13], v[216:219], v[136:139]
	v_mfma_f32_16x16x32_bf16 v[104:107], v[144:147], v[216:219], v[104:107]
	v_mfma_f32_16x16x32_bf16 v[132:135], v[10:13], v[224:227], v[132:135]
	v_mfma_f32_16x16x32_bf16 v[100:103], v[144:147], v[224:227], v[100:103]
	v_mfma_f32_16x16x32_bf16 v[128:131], v[10:13], v[242:245], v[128:131]
	v_mfma_f32_16x16x32_bf16 v[96:99], v[144:147], v[242:245], v[96:99]
	v_mfma_f32_16x16x32_bf16 v[124:127], v[10:13], v[250:253], v[124:127]
	v_mfma_f32_16x16x32_bf16 v[92:95], v[144:147], v[250:253], v[92:95]
	s_setprio 0

.Lgsk_9:
	s_barrier
	s_add_i32 s91, s91, s33
	v_lshl_add_u64 v[156:157], s[14:15], 0, v[160:161]
	s_mov_b32 m0, s91
	ds_read_b128 v[212:215], v206 offset:16384
	ds_read_b128 v[216:219], v206 offset:17408
	ds_read_b128 v[220:223], v206 offset:18432
	ds_read_b128 v[224:227], v206 offset:19456
	ds_read_b128 v[238:241], v206 offset:20480
	ds_read_b128 v[242:245], v206 offset:21504
	ds_read_b128 v[246:249], v206 offset:22528
	ds_read_b128 v[250:253], v206 offset:23552
	global_load_lds_dwordx4 v[156:157], off
	s_add_i32 m0, s91, 0x2000
	s_add_u32 vcc_lo, s14, 0x80000
	v_lshl_add_u64 v[184:185], s[14:15], 0, v[164:165]
	s_addc_u32 vcc_hi, s15, 0
	s_add_i32 s91, s96, s33
	global_load_lds_dwordx4 v[184:185], off
	v_lshl_add_u64 v[14:15], vcc, 0, v[160:161]
	s_mov_b32 m0, s91
	v_lshl_add_u64 v[196:197], s[52:53], 0, v[158:159]
	global_load_lds_dwordx4 v[14:15], off
	v_lshl_add_u64 v[14:15], vcc, 0, v[164:165]
	s_add_i32 m0, s91, 0x2000
	v_lshl_add_u64 v[198:199], s[52:53], 0, v[162:163]
	global_load_lds_dwordx4 v[14:15], off
	s_mov_b32 m0, s40
	s_nop 0
	global_load_lds_dwordx4 v[196:197], off
	s_mov_b32 m0, s41
	s_nop 0
	global_load_lds_dwordx4 v[198:199], off
	s_waitcnt vmcnt(8)
	s_waitcnt lgkmcnt(0)
	s_barrier
	s_bitcmp1_b32 s32, 1
	s_cbranch_scc1 .Lgsk_10
	s_setprio 1
	s_waitcnt lgkmcnt(0)
	v_mfma_f32_16x16x32_bf16 v[120:123], v[6:9], v[212:215], v[120:123]
	v_mfma_f32_16x16x32_bf16 v[88:91], v[140:143], v[212:215], v[88:91]
	v_mfma_f32_16x16x32_bf16 v[116:119], v[6:9], v[220:223], v[116:119]
	v_mfma_f32_16x16x32_bf16 v[84:87], v[140:143], v[220:223], v[84:87]
	v_mfma_f32_16x16x32_bf16 v[112:115], v[6:9], v[238:241], v[112:115]
	v_mfma_f32_16x16x32_bf16 v[80:83], v[140:143], v[238:241], v[80:83]
	v_mfma_f32_16x16x32_bf16 v[6:9], v[6:9], v[246:249], v[108:111]
	v_mfma_f32_16x16x32_bf16 v[120:123], v[10:13], v[216:219], v[120:123]
	v_mfma_f32_16x16x32_bf16 v[88:91], v[144:147], v[216:219], v[88:91]
	v_mfma_f32_16x16x32_bf16 v[116:119], v[10:13], v[224:227], v[116:119]
	v_mfma_f32_16x16x32_bf16 v[84:87], v[144:147], v[224:227], v[84:87]
	v_mfma_f32_16x16x32_bf16 v[112:115], v[10:13], v[242:245], v[112:115]
	v_mfma_f32_16x16x32_bf16 v[80:83], v[144:147], v[242:245], v[80:83]
	v_mfma_f32_16x16x32_bf16 v[6:9], v[10:13], v[250:253], v[6:9]
	v_mfma_f32_16x16x32_bf16 v[10:13], v[140:143], v[246:249], v[76:79]
	v_mfma_f32_16x16x32_bf16 v[10:13], v[144:147], v[250:253], v[10:13]
	s_setprio 0
.Lgsk_10:
	s_bitcmp1_b32 s32, 0
	s_cbranch_scc1 .Lgsk_11
	s_setprio 1
	v_mfma_f32_16x16x32_bf16 v[56:59], v[148:151], v[212:215], v[56:59]
	v_mfma_f32_16x16x32_bf16 v[24:27], v[180:183], v[212:215], v[24:27]
	v_mfma_f32_16x16x32_bf16 v[52:55], v[148:151], v[220:223], v[52:55]
	v_mfma_f32_16x16x32_bf16 v[20:23], v[180:183], v[220:223], v[20:23]
	v_mfma_f32_16x16x32_bf16 v[48:51], v[148:151], v[238:241], v[48:51]
	v_mfma_f32_16x16x32_bf16 v[14:17], v[180:183], v[238:241], v[16:19]
	v_mfma_f32_16x16x32_bf16 v[44:47], v[148:151], v[246:249], v[44:47]
	v_mfma_f32_16x16x32_bf16 v[2:5], v[180:183], v[246:249], v[2:5]
	v_mfma_f32_16x16x32_bf16 v[56:59], v[152:155], v[216:219], v[56:59]
	v_mfma_f32_16x16x32_bf16 v[24:27], v[208:211], v[216:219], v[24:27]
	v_mfma_f32_16x16x32_bf16 v[52:55], v[152:155], v[224:227], v[52:55]
	v_mfma_f32_16x16x32_bf16 v[20:23], v[208:211], v[224:227], v[20:23]
	v_mfma_f32_16x16x32_bf16 v[48:51], v[152:155], v[242:245], v[48:51]
	v_mfma_f32_16x16x32_bf16 v[14:17], v[208:211], v[242:245], v[14:17]
	v_mfma_f32_16x16x32_bf16 v[44:47], v[152:155], v[250:253], v[44:47]
	v_mfma_f32_16x16x32_bf16 v[2:5], v[208:211], v[250:253], v[2:5]
	s_setprio 0

.Lgsk_15:
	s_barrier
	s_add_i32 s90, s90, 2
	s_add_u32 s8, s8, 0x100
	s_addc_u32 s9, s9, 0
	s_add_u32 s68, s68, 0x100
	s_addc_u32 s69, s69, 0
	s_cmp_gt_u32 s90, 29
	s_cbranch_scc0 .LBB0_176
